# placement check with the writelane-to-readlane wait state fixed
# speedup vs baseline: 1.0004x; 1.0004x over previous
.LBB0_413:
	s_mov_b64 s[8:9], s[56:57]
	s_load_dword s1, s[8:9], 0x8c
	s_add_i32 s0, s91, 1
	s_mov_b64 s[6:7], -1
	s_waitcnt lgkmcnt(0)
	s_cmp_ge_i32 s0, s1
	s_cbranch_scc1 .LBB0_9
	s_cmp_eq_u32 s91, 0
	s_cbranch_scc1 .Lgb_full
	s_cmp_eq_u32 s91, 1
	s_cbranch_scc0 .Lchk_done
	s_load_dwordx2 s[4:5], s[56:57], 0x80
	v_and_b32_e32 v0, 63, v194
	v_lshlrev_b32_e32 v1, 2, v0
	v_and_b32_e32 v2, 7, v0
	v_lshlrev_b32_e32 v2, 2, v2
	s_waitcnt lgkmcnt(0)
	s_add_u32 s4, s4, 0x1d403800
	s_addc_u32 s5, s5, 0
	global_load_dword v3, v1, s[4:5] sc1
	global_load_dword v4, v1, s[4:5] offset:256 sc1
	global_load_dword v5, v1, s[4:5] offset:512 sc1
	global_load_dword v6, v1, s[4:5] offset:768 sc1
	global_load_dword v7, v2, s[4:5] sc1
	s_waitcnt vmcnt(0)
	v_xor_b32_e32 v3, v3, v7
	v_xor_b32_e32 v4, v4, v7
	v_xor_b32_e32 v5, v5, v7
	v_xor_b32_e32 v6, v6, v7
	v_or3_b32 v3, v3, v4, v5
	v_or_b32_e32 v3, v3, v6
	v_cmp_ne_u32_e32 vcc, 0, v3
	s_nop 1
	s_mov_b64 s[4:5], vcc
	v_cmp_eq_u32_e32 vcc, 0, v7
	s_nop 1
	s_or_b64 s[4:5], s[4:5], vcc
	s_cmp_eq_u64 s[4:5], 0
	s_cselect_b32 s4, 1, 0
	s_nop 0
	v_writelane_b32 v255, s4, 21
	s_nop 1
